# in-proj tile order rotated by 488 so the 24 gate-column tiles (slower compiler epilogue) land on workgroups that only run two tiles
# baseline (speedup 1.0000x reference)
.LBB0_345:
	s_waitcnt vmcnt(0) lgkmcnt(0)
	s_barrier
	s_add_i32 s6, s75, 0xa0
	s_add_i32 s75, s75, 0xfffffe18
	s_cmp_lt_i32 s75, 0
	s_cselect_b32 s75, s6, s75
	s_load_dword s6, s[78:79], 0x0
	s_waitcnt lgkmcnt(0)
	s_add_i32 s75, s6, s75
	s_cmpk_gt_i32 s75, 0x287
	s_cbranch_scc1 .LBB0_395
.LBB0_346:
	s_add_i32 s6, s75, 0xffffff60
	s_add_i32 s75, s75, 0x1e8
	s_cmpk_gt_i32 s75, 0x287
	s_cselect_b32 s75, s6, s75
	s_mul_hi_i32 s6, s75, 0x2aaaaaab
	s_lshr_b32 s13, s6, 31
	s_ashr_i32 s6, s6, 2
	s_add_i32 s6, s6, s13
	s_mul_i32 s13, s6, 24
	s_sub_i32 s13, s75, s13
	s_lshl_b32 s26, s13, 8
	s_ashr_i32 s27, s26, 31
	s_lshl_b64 s[34:35], s[26:27], 11
	s_mov_b32 m0, s11
	v_lshl_add_u64 v[2:3], v[106:107], 0, s[34:35]
	s_lshl_b32 s22, s6, 7
	global_load_lds_dwordx4 v[2:3], off
	v_lshl_add_u64 v[6:7], v[2:3], 0, s[30:31]
	s_add_i32 m0, s11, 0x400
	s_ashr_i32 s23, s22, 31
	global_load_lds_dwordx4 v[6:7], off
	v_lshl_add_u64 v[6:7], v[2:3], 0, s[24:25]
	s_add_i32 m0, s11, 0x800
	s_mov_b64 s[16:17], 0xc000
	s_lshl_b64 s[36:37], s[22:23], 11
	global_load_lds_dwordx4 v[6:7], off
	v_lshl_add_u64 v[6:7], v[2:3], 0, s[16:17]
	s_add_i32 m0, s11, 0xc00
	v_lshl_add_u64 v[4:5], v[108:109], 0, s[36:37]
	global_load_lds_dwordx4 v[6:7], off
	s_add_i32 m0, s12, 0x8000
	v_lshl_add_u64 v[6:7], v[4:5], 0, s[30:31]
	global_load_lds_dwordx4 v[4:5], off
	s_add_i32 m0, s12, 0x8400
	s_mov_b64 s[16:17], 0x4080
	global_load_lds_dwordx4 v[6:7], off
	v_lshl_add_u64 v[6:7], v[2:3], 0, s[2:3]
	s_add_i32 m0, s11, 0xc000
	s_mov_b64 s[46:47], 0x8080
	global_load_lds_dwordx4 v[6:7], off
	v_lshl_add_u64 v[6:7], v[2:3], 0, s[16:17]
	s_add_i32 m0, s11, 0xc400
	s_mov_b64 s[48:49], 0x8100
	global_load_lds_dwordx4 v[6:7], off
	v_lshl_add_u64 v[6:7], v[2:3], 0, s[46:47]
	s_add_i32 m0, s11, 0xc800
	s_mov_b64 s[46:47], 0xc080
	global_load_lds_dwordx4 v[6:7], off
	v_lshl_add_u64 v[6:7], v[2:3], 0, s[46:47]
	s_add_i32 m0, s11, 0xcc00
	s_mov_b64 s[46:47], 0x4100
	global_load_lds_dwordx4 v[6:7], off
	v_lshl_add_u64 v[6:7], v[4:5], 0, s[2:3]
	s_add_i32 m0, s12, 0x14000
	v_add_u32_e32 v117, v123, v124
	global_load_lds_dwordx4 v[6:7], off
	v_lshl_add_u64 v[6:7], v[4:5], 0, s[16:17]
	s_add_i32 m0, s12, 0x14400
	s_mov_b64 s[16:17], 0x100
	global_load_lds_dwordx4 v[6:7], off
	v_lshl_add_u64 v[6:7], v[2:3], 0, s[16:17]
	s_add_i32 m0, s11, 0x18000
	v_add_u32_e32 v221, v125, v124
	global_load_lds_dwordx4 v[6:7], off
	v_lshl_add_u64 v[6:7], v[2:3], 0, s[46:47]
	s_add_i32 m0, s11, 0x18400
	v_mov_b32_e32 v34, 0
	global_load_lds_dwordx4 v[6:7], off
	v_lshl_add_u64 v[6:7], v[2:3], 0, s[48:49]
	s_add_i32 m0, s11, 0x18800
	s_mov_b64 s[48:49], 0xc100
	global_load_lds_dwordx4 v[6:7], off
	v_lshl_add_u64 v[2:3], v[2:3], 0, s[48:49]
	s_add_i32 m0, s11, 0x18c00
	v_lshl_add_u64 v[118:119], v[104:105], 0, s[34:35]
	global_load_lds_dwordx4 v[2:3], off
	v_lshl_add_u64 v[2:3], v[4:5], 0, s[16:17]
	s_add_i32 m0, s12, 0x20000
	v_lshl_add_u64 v[120:121], v[114:115], 0, s[36:37]
	global_load_lds_dwordx4 v[2:3], off
	v_lshl_add_u64 v[2:3], v[4:5], 0, s[46:47]
	s_add_i32 m0, s12, 0x20400
	s_mov_b32 s6, -1
	global_load_lds_dwordx4 v[2:3], off
	s_waitcnt vmcnt(12)
	s_waitcnt lgkmcnt(0)
	s_barrier
	ds_read_b128 v[30:33], v117
	ds_read_b128 v[26:29], v221 offset:2048
	ds_read_b128 v[14:17], v221 offset:4096
	ds_read_b128 v[2:5], v221 offset:6144
	ds_read_b128 v[22:25], v210 offset:32768
	ds_read_b128 v[18:21], v212 offset:34816
	ds_read_b128 v[10:13], v212 offset:36864
	ds_read_b128 v[6:9], v212 offset:38912
	s_mov_b32 s13, 0
	s_mov_b32 s14, 1
	s_mov_b32 s19, 0
	v_mov_b32_e32 v35, v34
	v_mov_b32_e32 v36, v34
	v_mov_b32_e32 v37, v34
	v_mov_b32_e32 v42, v34
	v_mov_b32_e32 v43, v34
	v_mov_b32_e32 v44, v34
	v_mov_b32_e32 v45, v34
	v_mov_b32_e32 v46, v34
	v_mov_b32_e32 v47, v34
	v_mov_b32_e32 v48, v34
	v_mov_b32_e32 v49, v34
	v_mov_b32_e32 v50, v34
	v_mov_b32_e32 v51, v34
	v_mov_b32_e32 v52, v34
	v_mov_b32_e32 v53, v34
	v_mov_b32_e32 v54, v34
	v_mov_b32_e32 v55, v34
	v_mov_b32_e32 v56, v34
	v_mov_b32_e32 v57, v34
	v_mov_b32_e32 v58, v34
	v_mov_b32_e32 v59, v34
	v_mov_b32_e32 v60, v34
	v_mov_b32_e32 v61, v34
	v_mov_b32_e32 v62, v34
	v_mov_b32_e32 v63, v34
	v_mov_b32_e32 v64, v34
	v_mov_b32_e32 v65, v34
	v_mov_b32_e32 v66, v34
	v_mov_b32_e32 v67, v34
	v_mov_b32_e32 v68, v34
	v_mov_b32_e32 v69, v34
	v_mov_b32_e32 v70, v34
	v_mov_b32_e32 v71, v34
	v_mov_b32_e32 v72, v34
	v_mov_b32_e32 v73, v34
	v_mov_b32_e32 v74, v34
	v_mov_b32_e32 v75, v34
	v_mov_b32_e32 v76, v34
	v_mov_b32_e32 v77, v34
	v_mov_b32_e32 v78, v34
	v_mov_b32_e32 v79, v34
	v_mov_b32_e32 v80, v34
	v_mov_b32_e32 v81, v34
	v_mov_b32_e32 v82, v34
	v_mov_b32_e32 v83, v34
	v_mov_b32_e32 v84, v34
	v_mov_b32_e32 v85, v34
	v_mov_b32_e32 v94, v34
	v_mov_b32_e32 v95, v34
	v_mov_b32_e32 v96, v34
	v_mov_b32_e32 v97, v34
	v_mov_b32_e32 v86, v34
	v_mov_b32_e32 v87, v34
	v_mov_b32_e32 v88, v34
	v_mov_b32_e32 v89, v34
	v_mov_b32_e32 v90, v34
	v_mov_b32_e32 v91, v34
	v_mov_b32_e32 v92, v34
	v_mov_b32_e32 v93, v34
	v_mov_b32_e32 v38, v34
	v_mov_b32_e32 v39, v34
	v_mov_b32_e32 v40, v34
	v_mov_b32_e32 v41, v34
